# stack v62 + attention row-max exchanges via v_permlane16/32_swap + gmlp norm-weight loads hoisted into the first load batch
# baseline (speedup 1.0000x reference)
; #define LAS __attribute__((address_space(3)))
; __device__ __forceinline__ unsigned pk2s(float lo, float hi) { unsigned r; asm("s_nop 0\n\tv_cvt_pk_bf16_f32 %0, %1, %2" : "=v"(r) : "v"(lo), "v"(hi)); return r; }
; __device__ __forceinline__ float fexp2(float x) { return __builtin_amdgcn_exp2f(x); }
; __device__ __forceinline__ f32x4 mfma16(bf16x8 a, bf16x8 b, f32x4 c) { return __builtin_amdgcn_mfma_f32_16x16x32_bf16(a, b, c, 0, 0, 0); }
; __device__ __forceinline__ void attn_item(const Params& p, int l, int item, LAS unsigned char* lds) {
;     ...
;             for (int j = 0; j < 4; ++j) { const int dist = base - (kt * 16 + fq * 4 + j); const int idx = (dist < 256 ? dist : 256) + 63;
;                 const float sv = s[kt][j] * (0.125f * LOG2E) + bias_s[hh * 320 + idx]; s[kt][j] = sv; cmax = fmaxf(cmax, sv); }
;         cmax = fmaxf(cmax, __shfl_xor(cmax, 16)); cmax = fmaxf(cmax, __shfl_xor(cmax, 32));
;         const float mnew = fmaxf(mrun, cmax), alpha = fexp2(mrun - mnew); mrun = mnew;
;         float ps = 0.f;
; #pragma unroll
;         for (int kt = 0; kt < 4; ++kt)
; #pragma unroll
;             for (int j = 0; j < 4; ++j) { const float e = fexp2(s[kt][j] - mnew); s[kt][j] = e; ps += e; }
;         lsum = lsum * alpha + ps;
; #pragma unroll
;         for (int dt = 0; dt < 4; ++dt) o[dt] *= alpha;
; #pragma unroll
;         for (int i = 0; i < 2; ++i) {
;             u32x4 pw; pw.x = pk2s(s[2 * i][0], s[2 * i][1]); pw.y = pk2s(s[2 * i][2], s[2 * i][3]); pw.z = pk2s(s[2 * i + 1][0], s[2 * i + 1][1]); pw.w = pk2s(s[2 * i + 1][2], s[2 * i + 1][3]);
;             const bf16x8 pb = as_bf8(pw);
;             const LAS unsigned char* vp = Vb + (32 * i + 4 * fq + (fr >> 2)) * VST + hh * 128 + (fr & 3) * 8;
; #pragma unroll
;             for (int dt = 0; dt < 4; ++dt) {
;                 const v4i16_t a0 = __builtin_amdgcn_ds_read_tr16_b64_v4i16((LAS v4i16_t*)(vp + dt * 32));
;                 const v4i16_t a1 = __builtin_amdgcn_ds_read_tr16_b64_v4i16((LAS v4i16_t*)(vp + 16 * VST + dt * 32));
;                 const bf16x8 av = __builtin_shufflevector(a0, a1, 0, 1, 2, 3, 4, 5, 6, 7);
;                 o[dt] = mfma16(av, pb, o[dt]); }
;         }
;     }
.Lattn_near_c:
	v_fmac_f32_e32 v88, 0x3e38aa3b, v72
	v_fmac_f32_e32 v89, 0x3e38aa3b, v73
	v_fmac_f32_e32 v90, 0x3e38aa3b, v74
	v_fmac_f32_e32 v91, 0x3e38aa3b, v75
	v_fmac_f32_e32 v92, 0x3e38aa3b, v76
	v_fmac_f32_e32 v93, 0x3e38aa3b, v77
	v_fmac_f32_e32 v94, 0x3e38aa3b, v78
	v_fmac_f32_e32 v95, 0x3e38aa3b, v79
	v_fmac_f32_e32 v96, 0x3e38aa3b, v48
	v_fmac_f32_e32 v97, 0x3e38aa3b, v49
	v_fmac_f32_e32 v98, 0x3e38aa3b, v50
	v_fmac_f32_e32 v99, 0x3e38aa3b, v51
	s_nop 7
	v_fmac_f32_e32 v100, 0x3e38aa3b, v80
	v_fmac_f32_e32 v101, 0x3e38aa3b, v81
	v_fmac_f32_e32 v102, 0x3e38aa3b, v82
	v_fmac_f32_e32 v103, 0x3e38aa3b, v83
	v_max3_f32 v196, v88, s15, v89
	v_max3_f32 v196, v196, v90, v91
	v_max3_f32 v196, v196, v92, v93
	v_max3_f32 v196, v196, v94, v95
	v_max3_f32 v196, v196, v96, v97
	v_max3_f32 v196, v196, v98, v99
	v_max3_f32 v196, v196, v100, v101
	v_max3_f32 v196, v196, v102, v103
	v_mov_b32_e32 v197, v196
	s_nop 1
	v_permlane16_swap_b32_e32 v197, v196
	v_max_f32_e32 v197, v196, v197
	v_mov_b32_e32 v47, v197
	s_nop 1
	v_permlane32_swap_b32_e32 v47, v197
	v_max3_f32 v47, v70, v197, v47
	ds_read_b64_tr_b16 v[164:165], v69 offset:26624
	ds_read_b64_tr_b16 v[166:167], v69 offset:31232
	ds_read_b64_tr_b16 v[168:169], v69 offset:26656
	ds_read_b64_tr_b16 v[170:171], v69 offset:31264
	ds_read_b64_tr_b16 v[172:173], v69 offset:26688
	ds_read_b64_tr_b16 v[174:175], v69 offset:31296
	ds_read_b64_tr_b16 v[176:177], v69 offset:26720
	ds_read_b64_tr_b16 v[178:179], v69 offset:31328
	v_sub_f32_e32 v70, v70, v47
	v_sub_f32_e32 v88, v88, v47
	v_sub_f32_e32 v89, v89, v47
	v_sub_f32_e32 v90, v90, v47
	v_sub_f32_e32 v91, v91, v47
	v_sub_f32_e32 v92, v92, v47
	v_sub_f32_e32 v93, v93, v47
	v_sub_f32_e32 v94, v94, v47
	v_sub_f32_e32 v95, v95, v47
	v_sub_f32_e32 v96, v96, v47
	v_sub_f32_e32 v97, v97, v47
	v_sub_f32_e32 v98, v98, v47
	v_sub_f32_e32 v99, v99, v47
	v_sub_f32_e32 v100, v100, v47
	v_sub_f32_e32 v101, v101, v47
	v_sub_f32_e32 v102, v102, v47
	v_sub_f32_e32 v103, v103, v47
	v_exp_f32_e32 v44, v70
	v_exp_f32_e32 v88, v88
	v_exp_f32_e32 v89, v89
	v_exp_f32_e32 v90, v90
	v_exp_f32_e32 v91, v91
	v_exp_f32_e32 v92, v92
	v_exp_f32_e32 v93, v93
	v_exp_f32_e32 v94, v94
	v_exp_f32_e32 v95, v95
	v_exp_f32_e32 v96, v96
	v_exp_f32_e32 v97, v97
	v_exp_f32_e32 v98, v98
	v_exp_f32_e32 v99, v99
	v_exp_f32_e32 v100, v100
	v_exp_f32_e32 v101, v101
	v_exp_f32_e32 v102, v102
	v_exp_f32_e32 v103, v103
	v_pk_mul_f32 v[28:29], v[28:29], v[44:45] op_sel_hi:[1,0]
	v_pk_mul_f32 v[30:31], v[30:31], v[44:45] op_sel_hi:[1,0]
	v_pk_mul_f32 v[32:33], v[32:33], v[44:45] op_sel_hi:[1,0]
	v_pk_mul_f32 v[34:35], v[34:35], v[44:45] op_sel_hi:[1,0]
	v_pk_mul_f32 v[36:37], v[36:37], v[44:45] op_sel_hi:[1,0]
	v_pk_mul_f32 v[38:39], v[38:39], v[44:45] op_sel_hi:[1,0]
	v_pk_mul_f32 v[40:41], v[40:41], v[44:45] op_sel_hi:[1,0]
	v_pk_mul_f32 v[42:43], v[42:43], v[44:45] op_sel_hi:[1,0]
	v_add_f32_e32 v48, 0, v88
	v_add_f32_e32 v48, v89, v48
	v_add_f32_e32 v48, v90, v48
	v_add_f32_e32 v48, v91, v48
	v_add_f32_e32 v48, v92, v48
	v_add_f32_e32 v48, v93, v48
	v_add_f32_e32 v48, v94, v48
	v_add_f32_e32 v48, v95, v48
	v_add_f32_e32 v48, v96, v48
	v_add_f32_e32 v48, v97, v48
	v_add_f32_e32 v48, v98, v48
	v_add_f32_e32 v48, v99, v48
	v_add_f32_e32 v48, v100, v48
	v_add_f32_e32 v48, v101, v48
	v_add_f32_e32 v48, v102, v48
	v_add_f32_e32 v48, v103, v48
	v_fmac_f32_e32 v48, v68, v44
	v_cvt_pk_bf16_f32 v198, v88, v89
	v_cvt_pk_bf16_f32 v199, v90, v91
	v_cvt_pk_bf16_f32 v200, v92, v93
	v_cvt_pk_bf16_f32 v201, v94, v95
	v_cvt_pk_bf16_f32 v214, v96, v97
	v_cvt_pk_bf16_f32 v215, v98, v99
	v_cvt_pk_bf16_f32 v216, v100, v101
	v_cvt_pk_bf16_f32 v217, v102, v103
	s_add_i32 s15, s7, 1
	s_waitcnt lgkmcnt(8)
	v_mfma_f32_16x16x32_bf16 v[28:31], v[148:151], v[198:201], v[28:31]
	v_mfma_f32_16x16x32_bf16 v[32:35], v[152:155], v[198:201], v[32:35]
	v_mfma_f32_16x16x32_bf16 v[36:39], v[156:159], v[198:201], v[36:39]
	v_mfma_f32_16x16x32_bf16 v[40:43], v[160:163], v[198:201], v[40:43]
	s_waitcnt lgkmcnt(0)
	v_mfma_f32_16x16x32_bf16 v[28:31], v[164:167], v[214:217], v[28:31]
	v_mfma_f32_16x16x32_bf16 v[32:35], v[168:171], v[214:217], v[32:35]
	v_mfma_f32_16x16x32_bf16 v[36:39], v[172:175], v[214:217], v[36:39]
	v_mfma_f32_16x16x32_bf16 v[40:43], v[176:179], v[214:217], v[40:43]
	s_cmp_lt_u32 s7, 8
	s_cbranch_scc0 .LBB0_425
	v_mov_b32_e32 v70, v47
	v_mov_b32_e32 v68, v48
	s_mov_b32 s7, s15
	s_branch .LBB0_410
